# k41 + kernarg pointer loads hoisted out of the P0 x->bf16 loop
# speedup vs baseline: 1.0026x; 1.0026x over previous
; __device__ __forceinline__ unsigned cvt_pk_bf16(float lo, float hi) { unsigned r; asm volatile("v_cvt_pk_bf16_f32 %0, %1, %2" : "=v"(r) : "v"(lo), "v"(hi)); return r; }
; __device__ __forceinline__ unsigned cvt_pk_bf16(float lo, float hi) { const f32x2 v = {lo, hi}; const bf16x2_t b = __builtin_convertvector(v, bf16x2_t); return __builtin_bit_cast(unsigned, b); }
; __device__ __forceinline__ void p0_prologue(Frame& F) {
;     ...
;     bf16* XB = (bf16*)(ws + WS_XB); float* SS = (float*)(ws + WS_SS); bf16* PE = (bf16*)(ws + WS_PE);
; #pragma unroll 1
;     for (int m0 = gw; m0 < MT; m0 += 2 * NGW) {
;         f32x4 v[2][4], pv[2]; int mm[2];
; #pragma unroll
;         for (int q = 0; q < 2; ++q) {
;             const int m = (m0 + q * NGW < MT) ? m0 + q * NGW : m0; mm[q] = m;
;             const float* xrow = (m < MP) ? A.in[0] + (size_t)m * D : A.in[1] + (size_t)(m - MP) * D;
;             const float* prow = (m < MP) ? A.in[2] + (size_t)m * DPLE : A.in[3] + (size_t)(m - MP) * DPLE;
; #pragma unroll
;             for (int j = 0; j < 4; ++j) v[q][j] = *((const f32x4*)xrow + F.lane + 64 * j);
;             pv[q] = *((const f32x4*)prow + F.lane);
;         }
; #pragma unroll
;         for (int q = 0; q < 2; ++q) {
;             const int m = mm[q]; float s = 0.f;
; #pragma unroll
;             for (int j = 0; j < 4; ++j) s += (v[q][j][0] * v[q][j][0] + v[q][j][1] * v[q][j][1]) + (v[q][j][2] * v[q][j][2] + v[q][j][3] * v[q][j][3]);
;             s = wave_sum(s);
;             v2u* o8 = (v2u*)(XB + (size_t)m * D) + F.lane;
; #pragma unroll
;             for (int j = 0; j < 4; ++j) { v2u w; w.x = cvt_pk_bf16(v[q][j][0], v[q][j][1]); w.y = cvt_pk_bf16(v[q][j][2], v[q][j][3]); o8[64 * j] = w; }
;             if (F.lane < 16) SS[(size_t)m * 16 + F.lane] = (F.lane == 0) ? s : 0.f;
;             v2u w; w.x = cvt_pk_bf16(pv[q][0], pv[q][1]); w.y = cvt_pk_bf16(pv[q][2], pv[q][3]);
;             *((v2u*)(PE + (size_t)m * DPLE) + F.lane) = w;
;         }
.LBB0_183:
	s_cmpk_gt_i32 s10, 0x43ff
	s_cbranch_scc1 .LBB0_190
	s_load_dwordx8 s[80:87], s[0:1], 0x0
	s_waitcnt vmcnt(8)
	v_mbcnt_lo_u32_b32 v0, -1, 0
	v_mbcnt_hi_u32_b32 v0, -1, v0
	v_and_b32_e32 v1, 64, v0
	v_add_u32_e32 v1, 64, v1
	v_xor_b32_e32 v2, 1, v0
	v_cmp_lt_i32_e32 vcc, v2, v1
	v_and_b32_e32 v4, 63, v192
	s_mov_b64 s[4:5], 0xcb90000
	v_cndmask_b32_e32 v2, v0, v2, vcc
	s_waitcnt vmcnt(6)
	v_lshlrev_b32_e32 v30, 2, v2
	v_xor_b32_e32 v2, 2, v0
	v_cmp_lt_i32_e32 vcc, v2, v1
	v_cmp_eq_u32_e64 s[6:7], 0, v4
	s_waitcnt vmcnt(4)
	v_lshlrev_b32_e32 v36, 4, v4
	v_cndmask_b32_e32 v2, v0, v2, vcc
	v_lshlrev_b32_e32 v31, 2, v2
	v_xor_b32_e32 v2, 4, v0
	v_cmp_lt_i32_e32 vcc, v2, v1
	s_nop 1
	v_cndmask_b32_e32 v2, v0, v2, vcc
	v_lshlrev_b32_e32 v32, 2, v2
	v_xor_b32_e32 v2, 8, v0
	v_cmp_lt_i32_e32 vcc, v2, v1
	s_nop 1
	v_cndmask_b32_e32 v2, v0, v2, vcc
	v_lshlrev_b32_e32 v33, 2, v2
	v_xor_b32_e32 v2, 16, v0
	v_cmp_lt_i32_e32 vcc, v2, v1
	s_nop 1
	v_cndmask_b32_e32 v2, v0, v2, vcc
	v_lshlrev_b32_e32 v34, 2, v2
	v_xor_b32_e32 v2, 32, v0
	v_cmp_lt_i32_e32 vcc, v2, v1
	v_mov_b32_e32 v1, 0
	v_mov_b32_e32 v3, v1
	v_cndmask_b32_e32 v0, v0, v2, vcc
	v_lshlrev_b32_e32 v35, 2, v0
	v_lshlrev_b32_e32 v0, 3, v4
	v_lshl_add_u64 v[24:25], s[34:35], 0, v[0:1]
	v_lshlrev_b32_e32 v2, 2, v4
	v_lshl_add_u64 v[0:1], s[26:27], 0, v[0:1]
	v_cmp_gt_u32_e32 vcc, 16, v4
	v_lshl_add_u64 v[26:27], s[44:45], 0, v[2:3]
	v_lshl_add_u64 v[28:29], v[0:1], 0, s[4:5]
	s_waitcnt lgkmcnt(0)
	s_branch .LBB0_186

; __device__ __forceinline__ unsigned cvt_pk_bf16(float lo, float hi) { unsigned r; asm volatile("v_cvt_pk_bf16_f32 %0, %1, %2" : "=v"(r) : "v"(lo), "v"(hi)); return r; }
; __device__ __forceinline__ unsigned cvt_pk_bf16(float lo, float hi) { const f32x2 v = {lo, hi}; const bf16x2_t b = __builtin_convertvector(v, bf16x2_t); return __builtin_bit_cast(unsigned, b); }
; __device__ __forceinline__ void p0_prologue(Frame& F) {
;     ...
;     for (int m0 = gw; m0 < MT; m0 += 2 * NGW) {
;         f32x4 v[2][4], pv[2]; int mm[2];
; #pragma unroll
;         for (int q = 0; q < 2; ++q) {
;             const int m = (m0 + q * NGW < MT) ? m0 + q * NGW : m0; mm[q] = m;
;             const float* xrow = (m < MP) ? A.in[0] + (size_t)m * D : A.in[1] + (size_t)(m - MP) * D;
;             const float* prow = (m < MP) ? A.in[2] + (size_t)m * DPLE : A.in[3] + (size_t)(m - MP) * DPLE;
; #pragma unroll
;             for (int j = 0; j < 4; ++j) v[q][j] = *((const f32x4*)xrow + F.lane + 64 * j);
;             pv[q] = *((const f32x4*)prow + F.lane);
;         }
; #pragma unroll
;         for (int q = 0; q < 2; ++q) {
;             const int m = mm[q]; float s = 0.f;
; #pragma unroll
;             for (int j = 0; j < 4; ++j) s += (v[q][j][0] * v[q][j][0] + v[q][j][1] * v[q][j][1]) + (v[q][j][2] * v[q][j][2] + v[q][j][3] * v[q][j][3]);
;             s = wave_sum(s);
;             v2u* o8 = (v2u*)(XB + (size_t)m * D) + F.lane;
; #pragma unroll
;             for (int j = 0; j < 4; ++j) { v2u w; w.x = cvt_pk_bf16(v[q][j][0], v[q][j][1]); w.y = cvt_pk_bf16(v[q][j][2], v[q][j][3]); o8[64 * j] = w; }
;             if (F.lane < 16) SS[(size_t)m * 16 + F.lane] = (F.lane == 0) ? s : 0.f;
;             v2u w; w.x = cvt_pk_bf16(pv[q][0], pv[q][1]); w.y = cvt_pk_bf16(pv[q][2], pv[q][3]);
;             *((v2u*)(PE + (size_t)m * DPLE) + F.lane) = w;
;         }
.LBB0_186:
	s_add_i32 s4, s10, 0xffffc000
	s_ashr_i32 s11, s10, 31
	s_cmpk_lt_i32 s10, 0x4000
	s_cselect_b32 s5, s11, 0
	s_cselect_b32 s4, s10, s4
	s_cselect_b32 s12, s80, s82
	s_cselect_b32 s13, s81, s83
	s_cselect_b32 s18, s84, s86
	s_cselect_b32 s19, s85, s87
	s_lshl_b64 s[14:15], s[4:5], 12
	s_add_u32 s12, s12, s14
	s_addc_u32 s13, s13, s15
	global_load_dwordx4 v[38:41], v36, s[12:13] nt
	global_load_dwordx4 v[42:45], v36, s[12:13] offset:1024 nt
	global_load_dwordx4 v[46:49], v36, s[12:13] offset:2048 nt
	global_load_dwordx4 v[50:53], v36, s[12:13] offset:3072 nt
	s_lshl_b64 s[4:5], s[4:5], 10
	s_add_u32 s14, s18, s4
	s_addc_u32 s15, s19, s5
	s_add_i32 s4, s10, s3
	s_cmpk_lt_i32 s4, 0x4400
	s_cselect_b32 s12, s4, s10
	s_ashr_i32 s13, s12, 31
	s_add_i32 s5, s12, 0xffffc000
	s_cmpk_lt_i32 s12, 0x4000
	s_cselect_b32 s16, s12, s5
	s_cselect_b32 s17, s13, 0
	s_cselect_b32 s18, s80, s82
	s_cselect_b32 s19, s81, s83
	s_cselect_b32 s20, s84, s86
	s_cselect_b32 s21, s85, s87
	s_lshl_b64 s[88:89], s[16:17], 12
	s_add_u32 s18, s18, s88
	s_addc_u32 s19, s19, s89
	global_load_dwordx4 v[20:23], v36, s[14:15] nt
	global_load_dwordx4 v[16:19], v36, s[18:19] nt
	global_load_dwordx4 v[12:15], v36, s[18:19] offset:1024 nt
	global_load_dwordx4 v[4:7], v36, s[18:19] offset:2048 nt
	s_lshl_b64 s[14:15], s[16:17], 10
	s_add_u32 s14, s20, s14
	s_addc_u32 s15, s21, s15
	global_load_dwordx4 v[8:11], v36, s[18:19] offset:3072 nt
	global_load_dwordx4 v[0:3], v36, s[14:15] nt
	s_lshl_b64 s[14:15], s[10:11], 11
	s_waitcnt vmcnt(9)
	v_mul_f32_e32 v37, v39, v39
	v_mul_f32_e32 v54, v41, v41
	s_waitcnt vmcnt(8)
	v_mul_f32_e32 v55, v43, v43
	v_mul_f32_e32 v56, v45, v45
	s_waitcnt vmcnt(7)
	v_mul_f32_e32 v57, v47, v47
	v_mul_f32_e32 v58, v49, v49
	v_fmac_f32_e32 v37, v38, v38
	v_fmac_f32_e32 v54, v40, v40
	v_fmac_f32_e32 v55, v42, v42
	v_fmac_f32_e32 v56, v44, v44
	s_waitcnt vmcnt(6)
	v_mul_f32_e32 v59, v51, v51
	v_mul_f32_e32 v60, v53, v53
	v_fmac_f32_e32 v57, v46, v46
	v_fmac_f32_e32 v58, v48, v48
	v_add_f32_e32 v37, v37, v54
	v_add_f32_e32 v54, v55, v56
	v_fmac_f32_e32 v59, v50, v50
	v_fmac_f32_e32 v60, v52, v52
	v_add_f32_e32 v55, v57, v58
	v_add_f32_e32 v37, v37, v54
	v_add_f32_e32 v56, v59, v60
	v_add_f32_e32 v37, v37, v55
	v_add_f32_e32 v37, v37, v56
	ds_bpermute_b32 v54, v30, v37
	v_cvt_pk_bf16_f32 v38, v38, v39
	v_cvt_pk_bf16_f32 v39, v40, v41
	v_cvt_pk_bf16_f32 v40, v42, v43
	v_cvt_pk_bf16_f32 v41, v44, v45
	s_waitcnt lgkmcnt(0)
	v_add_f32_e32 v37, v37, v54
	ds_bpermute_b32 v54, v31, v37
	v_cvt_pk_bf16_f32 v42, v46, v47
	s_waitcnt lgkmcnt(0)
	v_add_f32_e32 v37, v37, v54
	ds_bpermute_b32 v54, v32, v37
	s_waitcnt lgkmcnt(0)
	v_add_f32_e32 v37, v37, v54
	ds_bpermute_b32 v56, v33, v37
	v_lshl_add_u64 v[54:55], v[24:25], 0, s[14:15]
	global_store_dwordx2 v[54:55], v[38:39], off sc1
	global_store_dwordx2 v[54:55], v[40:41], off offset:512 sc1
	v_cvt_pk_bf16_f32 v40, v50, v51
	v_cvt_pk_bf16_f32 v41, v52, v53
	s_waitcnt lgkmcnt(0)
	v_add_f32_e32 v37, v37, v56
	ds_bpermute_b32 v43, v34, v37
	global_store_dwordx2 v[54:55], v[40:41], off offset:1536 sc1
	s_waitcnt lgkmcnt(0)
	v_add_f32_e32 v37, v37, v43
	ds_bpermute_b32 v38, v35, v37
	v_cvt_pk_bf16_f32 v43, v48, v49
	global_store_dwordx2 v[54:55], v[42:43], off offset:1024 sc1
	s_and_saveexec_b64 s[14:15], vcc
	s_cbranch_execz .LBB0_188
	s_waitcnt lgkmcnt(0)
	v_add_f32_e32 v37, v37, v38
	s_lshl_b64 s[16:17], s[10:11], 6
	v_lshl_add_u64 v[38:39], v[26:27], 0, s[16:17]
	v_cndmask_b32_e64 v37, 0, v37, s[6:7]
	global_store_dword v[38:39], v37, off
